# v19
# speedup vs baseline: 1.0048x; 1.0048x over previous
; #define WAIT_V(n) asm volatile("s_waitcnt vmcnt(%0)" ::"n"(n) : "memory")
; #define STAGE(P, BASE, OFF, kt) do { \
;     __builtin_amdgcn_global_load_lds((const unsigned*)((BASE) + (OFF[0] + (unsigned)(kt) * BK)), (unsigned*)((char*)(P) + wid * 1024), 16, 0, 0); \
;     __builtin_amdgcn_global_load_lds((const unsigned*)((BASE) + (OFF[1] + (unsigned)(kt) * BK)), (unsigned*)((char*)(P) + wid * 1024 + 8192), 16, 0, 0); } while (0)
; #define BAR __builtin_amdgcn_s_barrier()
; DEVI void gemm_tile(const Params& p, int layer, const u16* __restrict__ A, unsigned lda, const u16* __restrict__ Bt, unsigned ldb, int K,
;                     int brow, int bcol, int ekind, const int tid_) {
;     ...
;   const int wid = tid_ >> 6, lane = tid_ & 63, wr = wid >> 2, wc = wid & 3, fr = lane & 15, fq = lane >> 4;
;   unsigned offA[2], offB[2];
; #pragma unroll
;   for (int i = 0; i < 2; ++i) { int R, C; stage_rc8(tid_ * 16 + i * 8192, R, C); offA[i] = (unsigned)R * lda + C; offB[i] = (unsigned)R * ldb + C; }
;   const u16* A0 = A + (size_t)brow * lda; const u16* A1 = A + (size_t)(brow + HALF) * lda;
;   const u16* B0p = Bt + (size_t)bcol * ldb; const u16* B1p = Bt + (size_t)(bcol + HALF) * ldb;
;   f32x4 acc[2][2][4][2] = {};
;   bf16x8 At[4][2], B0[2][2], B1[2][2];
;   const int nt = K / BK;
;   STAGE(SB(0, 0), B0p, offB, 0); STAGE(SA(0, 0), A0, offA, 0);
;   STAGE(SB(0, 1), B1p, offB, 0); STAGE(SA(0, 1), A1, offA, 0);
;   if (wr == 1) BAR;
;   WAIT_V(4); BAR;
;   STAGE(SB(1, 0), B0p, offB, 1); STAGE(SA(1, 0), A0, offA, 1); STAGE(SB(1, 1), B1p, offB, 1);
;   WAIT_V(6); BAR;
.LBB0_312:
	s_or_b64 exec, exec, s[10:11]
	v_readlane_b32 s42, v254, 45
	v_add_u32_e32 v0, 64, v0
	v_lshlrev_b64 v[12:13], 1, v[0:1]
	v_add_u32_e32 v153, s42, v10
	v_lshl_add_u64 v[14:15], s[6:7], 0, v[12:13]
	v_readfirstlane_b32 s11, v153
	s_mov_b32 m0, s11
	v_add_u32_e32 v0, 64, v134
	v_add_u32_e32 v154, 0x2000, v153
	s_waitcnt vmcnt(4)
	s_barrier
	global_load_lds_dwordx4 v[14:15], off
	v_lshlrev_b64 v[14:15], 1, v[0:1]
	v_readfirstlane_b32 s11, v154
	v_add_u32_e32 v155, 0x8000, v145
	v_lshl_add_u64 v[16:17], s[6:7], 0, v[14:15]
	s_mov_b32 m0, s11
	v_add_u32_e32 v0, 64, v130
	v_readfirstlane_b32 s11, v155
	v_add_u32_e32 v157, 0xa000, v145
	v_readlane_b32 s45, v254, 46
	global_load_lds_dwordx4 v[16:17], off
	v_lshl_add_u64 v[16:17], v[0:1], 1, s[4:5]
	s_mov_b32 m0, s11
	v_add_u32_e32 v0, 64, v132
	v_readfirstlane_b32 s11, v157
	v_add_u32_e32 v158, s45, v10
	global_load_lds_dwordx4 v[16:17], off
	v_lshl_add_u64 v[16:17], v[0:1], 1, s[4:5]
	s_mov_b32 m0, s11
	v_readfirstlane_b32 s11, v158
	v_add_u32_e32 v159, 0x2000, v158
	global_load_lds_dwordx4 v[16:17], off
	v_lshl_add_u64 v[12:13], s[8:9], 0, v[12:13]
	s_mov_b32 m0, s11
	v_readfirstlane_b32 s11, v159
	global_load_lds_dwordx4 v[12:13], off
	v_lshl_add_u64 v[12:13], s[8:9], 0, v[14:15]
	s_mov_b32 m0, s11
	v_and_b32_e32 v135, 15, v136
	global_load_lds_dwordx4 v[12:13], off
	v_bfe_u32 v133, v136, 4, 2
	v_lshlrev_b32_e32 v12, 2, v136
	v_and_b32_e32 v131, 3, v9
	v_lshlrev_b32_e32 v9, 4, v133
	v_lshlrev_b32_e32 v10, 6, v135
	v_and_b32_e32 v12, 32, v12
	v_lshlrev_b32_e32 v17, 6, v136
	s_movk_i32 s11, 0x3c0
	s_waitcnt vmcnt(6)
	v_bitop3_b32 v10, v9, v12, v10 bitop3:0x36
	v_lshlrev_b32_e32 v137, 6, v11
	v_lshlrev_b32_e32 v11, 13, v11
	v_and_or_b32 v9, v17, s11, v9
	s_lshr_b32 s10, s66, 6
	v_lshlrev_b32_e32 v0, 12, v131
	v_add_u32_e32 v13, s31, v10
	v_add_u32_e32 v14, s50, v10
	v_add_u32_e32 v15, s42, v10
	v_add_u32_e32 v16, s45, v10
	v_add_u32_e32 v10, 0, v10
	v_xad_u32 v9, v9, v12, 0
	v_or_b32_e32 v12, 0x800, v11
	v_or_b32_e32 v17, 0x1000, v11
	v_or_b32_e32 v18, 0x1800, v11
	v_add3_u32 v162, v4, v2, v3
	v_add3_u32 v163, v5, v2, v3
	v_mov_b32_e32 v2, 0
	s_add_i32 s10, s10, -2
	v_add3_u32 v160, v8, v6, v7
	s_mov_b32 s11, 0
	v_add_u32_e32 v161, v13, v0
	v_add_u32_e32 v141, v10, v11
	v_add_u32_e32 v140, v9, v12
	v_add_u32_e32 v139, v9, v17
	v_add_u32_e32 v138, v9, v18
	v_add_u32_e32 v156, v14, v0
	v_add_u32_e32 v147, v15, v0
	v_add_u32_e32 v142, v16, v0
	s_mov_b32 s42, 0
	v_mov_b32_e32 v3, v2
	v_mov_b32_e32 v4, v2
	v_mov_b32_e32 v5, v2
	v_mov_b32_e32 v6, v2
	v_mov_b32_e32 v7, v2
	v_mov_b32_e32 v8, v2
	v_mov_b32_e32 v9, v2
	v_mov_b32_e32 v10, v2
	v_mov_b32_e32 v11, v2
	v_mov_b32_e32 v12, v2
	v_mov_b32_e32 v13, v2
	v_mov_b32_e32 v14, v2
	v_mov_b32_e32 v15, v2
	v_mov_b32_e32 v16, v2
	v_mov_b32_e32 v17, v2
	v_mov_b32_e32 v18, v2
	v_mov_b32_e32 v19, v2
	v_mov_b32_e32 v20, v2
	v_mov_b32_e32 v21, v2
	v_mov_b32_e32 v22, v2
	v_mov_b32_e32 v23, v2
	v_mov_b32_e32 v24, v2
	v_mov_b32_e32 v25, v2
	v_mov_b32_e32 v26, v2
	v_mov_b32_e32 v27, v2
	v_mov_b32_e32 v28, v2
	v_mov_b32_e32 v29, v2
	v_mov_b32_e32 v30, v2
	v_mov_b32_e32 v31, v2
	v_mov_b32_e32 v32, v2
	v_mov_b32_e32 v33, v2
	v_mov_b32_e32 v34, v2
	v_mov_b32_e32 v35, v2
	v_mov_b32_e32 v36, v2
	v_mov_b32_e32 v37, v2
	v_mov_b32_e32 v38, v2
	v_mov_b32_e32 v39, v2
	v_mov_b32_e32 v40, v2
	v_mov_b32_e32 v41, v2
	v_mov_b32_e32 v42, v2
	v_mov_b32_e32 v43, v2
	v_mov_b32_e32 v44, v2
	v_mov_b32_e32 v45, v2
	v_mov_b32_e32 v46, v2
	v_mov_b32_e32 v47, v2
	v_mov_b32_e32 v48, v2
	v_mov_b32_e32 v49, v2
	v_mov_b32_e32 v50, v2
	v_mov_b32_e32 v51, v2
	v_mov_b32_e32 v52, v2
	v_mov_b32_e32 v53, v2
	v_mov_b32_e32 v54, v2
	v_mov_b32_e32 v55, v2
	v_mov_b32_e32 v56, v2
	v_mov_b32_e32 v57, v2
	v_mov_b32_e32 v58, v2
	v_mov_b32_e32 v59, v2
	v_mov_b32_e32 v60, v2
	v_mov_b32_e32 v61, v2
	v_mov_b32_e32 v62, v2
	v_mov_b32_e32 v63, v2
	v_mov_b32_e32 v64, v2
	v_mov_b32_e32 v65, v2
	v_mov_b32_e32 v66, v2
	v_mov_b32_e32 v67, v2
	v_mov_b32_e32 v68, v2
	v_mov_b32_e32 v69, v2
	v_mov_b32_e32 v70, v2
	v_mov_b32_e32 v71, v2
	v_mov_b32_e32 v72, v2
	v_mov_b32_e32 v73, v2
	v_mov_b32_e32 v74, v2
	v_mov_b32_e32 v75, v2
	v_mov_b32_e32 v76, v2
	v_mov_b32_e32 v77, v2
	v_mov_b32_e32 v78, v2
	v_mov_b32_e32 v79, v2
	v_mov_b32_e32 v80, v2
	v_mov_b32_e32 v81, v2
	v_mov_b32_e32 v82, v2
	v_mov_b32_e32 v83, v2
	v_mov_b32_e32 v84, v2
	v_mov_b32_e32 v85, v2
	v_mov_b32_e32 v86, v2
	v_mov_b32_e32 v87, v2
	v_mov_b32_e32 v88, v2
	v_mov_b32_e32 v89, v2
	v_mov_b32_e32 v90, v2
	v_mov_b32_e32 v91, v2
	v_mov_b32_e32 v92, v2
	v_mov_b32_e32 v93, v2
	v_mov_b32_e32 v94, v2
	v_mov_b32_e32 v95, v2
	v_mov_b32_e32 v96, v2
	v_mov_b32_e32 v97, v2
	v_mov_b32_e32 v98, v2
	v_mov_b32_e32 v99, v2
	v_mov_b32_e32 v100, v2
	v_mov_b32_e32 v101, v2
	v_mov_b32_e32 v102, v2
	v_mov_b32_e32 v103, v2
	v_mov_b32_e32 v104, v2
	v_mov_b32_e32 v105, v2
	v_mov_b32_e32 v106, v2
	v_mov_b32_e32 v107, v2
	v_mov_b32_e32 v108, v2
	v_mov_b32_e32 v109, v2
	v_mov_b32_e32 v110, v2
	v_mov_b32_e32 v111, v2
	v_mov_b32_e32 v112, v2
	v_mov_b32_e32 v113, v2
	v_mov_b32_e32 v114, v2
	v_mov_b32_e32 v115, v2
	v_mov_b32_e32 v116, v2
	v_mov_b32_e32 v117, v2
	v_mov_b32_e32 v118, v2
	v_mov_b32_e32 v119, v2
	v_mov_b32_e32 v120, v2
	v_mov_b32_e32 v121, v2
	v_mov_b32_e32 v122, v2
	v_mov_b32_e32 v123, v2
	v_mov_b32_e32 v124, v2
	v_mov_b32_e32 v125, v2
	v_mov_b32_e32 v126, v2
	v_mov_b32_e32 v127, v2
	v_mov_b32_e32 v128, v2
	v_mov_b32_e32 v129, v2
	s_barrier
	v_readfirstlane_b32 s45, v145
; #define WAIT_L(n) asm volatile("s_waitcnt lgkmcnt(%0)" ::"n"(n) : "memory")
; #define STAGE(P, BASE, OFF, kt) do { \
;     __builtin_amdgcn_global_load_lds((const unsigned*)((BASE) + (OFF[0] + (unsigned)(kt) * BK)), (unsigned*)((char*)(P) + wid * 1024), 16, 0, 0); \
;     __builtin_amdgcn_global_load_lds((const unsigned*)((BASE) + (OFF[1] + (unsigned)(kt) * BK)), (unsigned*)((char*)(P) + wid * 1024 + 8192), 16, 0, 0); } while (0)
; #define LDA(dst, b, h) for (int m = 0; m < 4; ++m) for (int k = 0; k < 2; ++k) \
;     dst[m][k] = *reinterpret_cast<const bf16x8*>((char*)SA(b, h) + lds_byte(wr * 64 + m * 16 + fr, k * 32 + fq * 8))
; #define LDB(dst, b, h) for (int n = 0; n < 2; ++n) for (int k = 0; k < 2; ++k) \
;     dst[n][k] = *reinterpret_cast<const bf16x8*>((char*)SB(b, h) + lds_byte(wc * 32 + n * 16 + fr, k * 32 + fq * 8))
; #define MMA(ai, bj, At_, Bt_) do { __builtin_amdgcn_s_setprio(1); \
;     for (int m = 0; m < 4; ++m) for (int n = 0; n < 2; ++n) for (int k = 0; k < 2; ++k) \
;       acc[ai][bj][m][n] = __builtin_amdgcn_mfma_f32_16x16x32_bf16(Bt_[n][k], At_[m][k], acc[ai][bj][m][n], 0, 0, 0); \
;     __builtin_amdgcn_s_setprio(0); } while (0)
; #define BAR __builtin_amdgcn_s_barrier()
; #define SCHED __builtin_amdgcn_sched_barrier(0)
; DEVI void gemm_tile(const Params& p, int layer, const u16* __restrict__ A, unsigned lda, const u16* __restrict__ Bt, unsigned ldb, int K,
;                     int brow, int bcol, int ekind, const int tid_) {
;     ...
;     LDB(B0, 0, 0); SCHED; LDA(At, 0, 0); STAGE(SA(1, 1), A1, offA, t + 1);
;     WAIT_L(8); BAR; WAIT_L(0); MMA(0, 0, At, B0); BAR; SCHED;
;     LDB(B1, 0, 1); STAGE(SB(0, 0), B0p, offB, t + 2);
;     BAR; WAIT_L(0); MMA(0, 1, At, B1); BAR;
;     LDA(At, 0, 1); STAGE(SA(0, 0), A0, offA, t + 2);
;     BAR; WAIT_L(0); MMA(1, 0, At, B0); BAR; SCHED;
.LBB0_313:
	ds_read_b128 v[180:183], v161
	ds_read_b128 v[184:187], v161 offset:1024
	ds_read_b128 v[188:191], v161 offset:2048
	ds_read_b128 v[192:195], v161 offset:3072
	v_add_u32_e32 v168, s11, v162
	v_add_u32_e32 v164, 0xc000, v145
	v_add_u32_e32 v0, 64, v168
	v_add_u32_e32 v179, s11, v160
	v_add_u32_e32 v165, 0xe000, v145
	v_lshl_add_u64 v[166:167], v[0:1], 1, s[2:3]
	s_add_i32 m0, s45, 0xc000
	v_add_u32_e32 v0, 64, v179
	ds_read_b128 v[196:199], v141
	ds_read_b128 v[200:203], v141 offset:1024
	ds_read_b128 v[204:207], v140
	ds_read_b128 v[208:211], v140 offset:1024
	ds_read_b128 v[212:215], v139
	ds_read_b128 v[216:219], v139 offset:1024
	ds_read_b128 v[220:223], v138
	ds_read_b128 v[224:227], v138 offset:1024
	global_load_lds_dwordx4 v[166:167], off
	s_add_i32 m0, s45, 0xe000
	v_lshl_add_u64 v[166:167], v[0:1], 1, s[2:3]
	global_load_lds_dwordx4 v[166:167], off
	s_waitcnt lgkmcnt(8)
	s_barrier
	s_waitcnt lgkmcnt(0)
	s_setprio 1
	v_mfma_f32_16x16x32_bf16 v[126:129], v[180:183], v[196:199], v[126:129]
	v_mfma_f32_16x16x32_bf16 v[122:125], v[188:191], v[196:199], v[122:125]
	v_mfma_f32_16x16x32_bf16 v[118:121], v[180:183], v[204:207], v[118:121]
	v_mfma_f32_16x16x32_bf16 v[114:117], v[188:191], v[204:207], v[114:117]
	v_mfma_f32_16x16x32_bf16 v[110:113], v[180:183], v[212:215], v[110:113]
	v_mfma_f32_16x16x32_bf16 v[106:109], v[188:191], v[212:215], v[106:109]
	v_mfma_f32_16x16x32_bf16 v[102:105], v[180:183], v[220:223], v[102:105]
	v_mfma_f32_16x16x32_bf16 v[98:101], v[188:191], v[220:223], v[98:101]
	v_mfma_f32_16x16x32_bf16 v[126:129], v[184:187], v[200:203], v[126:129]
	v_mfma_f32_16x16x32_bf16 v[122:125], v[192:195], v[200:203], v[122:125]
	v_mfma_f32_16x16x32_bf16 v[118:121], v[184:187], v[208:211], v[118:121]
	v_mfma_f32_16x16x32_bf16 v[114:117], v[192:195], v[208:211], v[114:117]
	v_mfma_f32_16x16x32_bf16 v[110:113], v[184:187], v[216:219], v[110:113]
	v_mfma_f32_16x16x32_bf16 v[106:109], v[192:195], v[216:219], v[106:109]
	v_mfma_f32_16x16x32_bf16 v[102:105], v[184:187], v[224:227], v[102:105]
	v_mfma_f32_16x16x32_bf16 v[98:101], v[192:195], v[224:227], v[98:101]
	s_setprio 0
	s_barrier
	v_add_u32_e32 v252, s11, v163
	v_add_u32_e32 v0, 0x80, v252
	v_lshlrev_b64 v[166:167], 1, v[0:1]
	v_add_u32_e32 v169, s11, v134
	v_lshl_add_u64 v[244:245], s[6:7], 0, v[166:167]
	s_add_i32 m0, s45, 0x10000
	v_add_u32_e32 v0, 0x80, v169
	ds_read_b128 v[228:231], v156
	ds_read_b128 v[232:235], v156 offset:1024
	ds_read_b128 v[236:239], v156 offset:2048
	ds_read_b128 v[240:243], v156 offset:3072
	global_load_lds_dwordx4 v[244:245], off
	v_lshlrev_b64 v[244:245], 1, v[0:1]
	v_lshl_add_u64 v[246:247], s[6:7], 0, v[244:245]
	s_add_i32 m0, s45, 0x12000
	s_add_i32 s42, s42, 2
	global_load_lds_dwordx4 v[246:247], off
	s_barrier
	s_waitcnt lgkmcnt(0)
	s_setprio 1
	v_mfma_f32_16x16x32_bf16 v[94:97], v[228:231], v[196:199], v[94:97]
	v_mfma_f32_16x16x32_bf16 v[90:93], v[236:239], v[196:199], v[90:93]
	v_mfma_f32_16x16x32_bf16 v[86:89], v[228:231], v[204:207], v[86:89]
	v_mfma_f32_16x16x32_bf16 v[82:85], v[236:239], v[204:207], v[82:85]
	v_mfma_f32_16x16x32_bf16 v[78:81], v[228:231], v[212:215], v[78:81]
	v_mfma_f32_16x16x32_bf16 v[74:77], v[236:239], v[212:215], v[74:77]
	v_mfma_f32_16x16x32_bf16 v[70:73], v[228:231], v[220:223], v[70:73]
	v_mfma_f32_16x16x32_bf16 v[66:69], v[236:239], v[220:223], v[66:69]
	v_mfma_f32_16x16x32_bf16 v[94:97], v[232:235], v[200:203], v[94:97]
	v_mfma_f32_16x16x32_bf16 v[90:93], v[240:243], v[200:203], v[90:93]
	v_mfma_f32_16x16x32_bf16 v[86:89], v[232:235], v[208:211], v[86:89]
	v_mfma_f32_16x16x32_bf16 v[82:85], v[240:243], v[208:211], v[82:85]
	v_mfma_f32_16x16x32_bf16 v[78:81], v[232:235], v[216:219], v[78:81]
	v_mfma_f32_16x16x32_bf16 v[74:77], v[240:243], v[216:219], v[74:77]
	v_mfma_f32_16x16x32_bf16 v[70:73], v[232:235], v[224:227], v[70:73]
	v_mfma_f32_16x16x32_bf16 v[66:69], v[240:243], v[224:227], v[66:69]
	s_setprio 0
	v_add_u32_e32 v0, 0x80, v168
	v_lshlrev_b64 v[246:247], 1, v[0:1]
	v_lshl_add_u64 v[248:249], s[4:5], 0, v[246:247]
	s_mov_b32 m0, s45
	v_add_u32_e32 v0, 0x80, v179
	s_barrier
	ds_read_b128 v[196:199], v141 offset:16384
	ds_read_b128 v[200:203], v141 offset:17408
	ds_read_b128 v[204:207], v140 offset:16384
	ds_read_b128 v[208:211], v140 offset:17408
	ds_read_b128 v[212:215], v139 offset:16384
	ds_read_b128 v[216:219], v139 offset:17408
	ds_read_b128 v[220:223], v138 offset:16384
	ds_read_b128 v[224:227], v138 offset:17408
	global_load_lds_dwordx4 v[248:249], off
	v_lshlrev_b64 v[248:249], 1, v[0:1]
	s_add_i32 m0, s45, 0x2000
	v_lshl_add_u64 v[250:251], s[4:5], 0, v[248:249]
	global_load_lds_dwordx4 v[250:251], off
	s_barrier
	s_waitcnt lgkmcnt(0)
	s_setprio 1
	v_mfma_f32_16x16x32_bf16 v[62:65], v[180:183], v[196:199], v[62:65]
	v_mfma_f32_16x16x32_bf16 v[58:61], v[188:191], v[196:199], v[58:61]
	v_mfma_f32_16x16x32_bf16 v[54:57], v[180:183], v[204:207], v[54:57]
	v_mfma_f32_16x16x32_bf16 v[50:53], v[188:191], v[204:207], v[50:53]
	v_mfma_f32_16x16x32_bf16 v[46:49], v[180:183], v[212:215], v[46:49]
	v_mfma_f32_16x16x32_bf16 v[42:45], v[188:191], v[212:215], v[42:45]
	v_mfma_f32_16x16x32_bf16 v[38:41], v[180:183], v[220:223], v[38:41]
	v_mfma_f32_16x16x32_bf16 v[34:37], v[188:191], v[220:223], v[34:37]
	v_mfma_f32_16x16x32_bf16 v[62:65], v[184:187], v[200:203], v[62:65]
	v_mfma_f32_16x16x32_bf16 v[58:61], v[192:195], v[200:203], v[58:61]
	v_mfma_f32_16x16x32_bf16 v[54:57], v[184:187], v[208:211], v[54:57]
	v_mfma_f32_16x16x32_bf16 v[50:53], v[192:195], v[208:211], v[50:53]
	v_mfma_f32_16x16x32_bf16 v[46:49], v[184:187], v[216:219], v[46:49]
	v_mfma_f32_16x16x32_bf16 v[42:45], v[192:195], v[216:219], v[42:45]
	v_mfma_f32_16x16x32_bf16 v[38:41], v[184:187], v[224:227], v[38:41]
	v_mfma_f32_16x16x32_bf16 v[34:37], v[192:195], v[224:227], v[34:37]
	s_setprio 0
	s_barrier
; #define WAIT_V(n) asm volatile("s_waitcnt vmcnt(%0)" ::"n"(n) : "memory")
; #define WAIT_L(n) asm volatile("s_waitcnt lgkmcnt(%0)" ::"n"(n) : "memory")
; #define STAGE(P, BASE, OFF, kt) do { \
;     __builtin_amdgcn_global_load_lds((const unsigned*)((BASE) + (OFF[0] + (unsigned)(kt) * BK)), (unsigned*)((char*)(P) + wid * 1024), 16, 0, 0); \
;     __builtin_amdgcn_global_load_lds((const unsigned*)((BASE) + (OFF[1] + (unsigned)(kt) * BK)), (unsigned*)((char*)(P) + wid * 1024 + 8192), 16, 0, 0); } while (0)
; #define LDA(dst, b, h) for (int m = 0; m < 4; ++m) for (int k = 0; k < 2; ++k) \
;     dst[m][k] = *reinterpret_cast<const bf16x8*>((char*)SA(b, h) + lds_byte(wr * 64 + m * 16 + fr, k * 32 + fq * 8))
; #define LDB(dst, b, h) for (int n = 0; n < 2; ++n) for (int k = 0; k < 2; ++k) \
;     dst[n][k] = *reinterpret_cast<const bf16x8*>((char*)SB(b, h) + lds_byte(wc * 32 + n * 16 + fr, k * 32 + fq * 8))
; #define MMA(ai, bj, At_, Bt_) do { __builtin_amdgcn_s_setprio(1); \
;     for (int m = 0; m < 4; ++m) for (int n = 0; n < 2; ++n) for (int k = 0; k < 2; ++k) \
;       acc[ai][bj][m][n] = __builtin_amdgcn_mfma_f32_16x16x32_bf16(Bt_[n][k], At_[m][k], acc[ai][bj][m][n], 0, 0, 0); \
;     __builtin_amdgcn_s_setprio(0); } while (0)
; #define BAR __builtin_amdgcn_s_barrier()
; #define SCHED __builtin_amdgcn_sched_barrier(0)
; DEVI void gemm_tile(const Params& p, int layer, const u16* __restrict__ A, unsigned lda, const u16* __restrict__ Bt, unsigned ldb, int K,
;                     int brow, int bcol, int ekind, const int tid_) {
;     ...
;     STAGE(SB(0, 1), B1p, offB, t + 2);
;     WAIT_V(6); BAR; MMA(1, 1, At, B1); BAR;
;     LDB(B0, 1, 0); SCHED; LDA(At, 1, 0); STAGE(SA(0, 1), A1, offA, t + 2);
;     WAIT_L(8); BAR; WAIT_L(0); MMA(0, 0, At, B0); BAR; SCHED;
;     LDB(B1, 1, 1); STAGE(SB(1, 0), B0p, offB, t + 3);
;     BAR; WAIT_L(0); MMA(0, 1, At, B1); BAR;
;     LDA(At, 1, 1); STAGE(SA(1, 0), A0, offA, t + 3);
	v_lshl_add_u64 v[166:167], s[8:9], 0, v[166:167]
	s_add_i32 m0, s45, 0x14000
	s_nop 0
	global_load_lds_dwordx4 v[166:167], off
	s_add_i32 m0, s45, 0x16000
	v_lshl_add_u64 v[166:167], s[8:9], 0, v[244:245]
	global_load_lds_dwordx4 v[166:167], off
	s_waitcnt vmcnt(6)
	s_barrier
	s_setprio 1
	v_mfma_f32_16x16x32_bf16 v[30:33], v[228:231], v[196:199], v[30:33]
	v_mfma_f32_16x16x32_bf16 v[26:29], v[236:239], v[196:199], v[26:29]
	v_mfma_f32_16x16x32_bf16 v[22:25], v[228:231], v[204:207], v[22:25]
	v_mfma_f32_16x16x32_bf16 v[18:21], v[236:239], v[204:207], v[18:21]
	v_mfma_f32_16x16x32_bf16 v[14:17], v[228:231], v[212:215], v[14:17]
	v_mfma_f32_16x16x32_bf16 v[10:13], v[236:239], v[212:215], v[10:13]
	v_mfma_f32_16x16x32_bf16 v[6:9], v[228:231], v[220:223], v[6:9]
	v_mfma_f32_16x16x32_bf16 v[2:5], v[236:239], v[220:223], v[2:5]
	v_mfma_f32_16x16x32_bf16 v[30:33], v[232:235], v[200:203], v[30:33]
	v_mfma_f32_16x16x32_bf16 v[26:29], v[240:243], v[200:203], v[26:29]
	v_mfma_f32_16x16x32_bf16 v[22:25], v[232:235], v[208:211], v[22:25]
	v_mfma_f32_16x16x32_bf16 v[18:21], v[240:243], v[208:211], v[18:21]
	v_mfma_f32_16x16x32_bf16 v[14:17], v[232:235], v[216:219], v[14:17]
	v_mfma_f32_16x16x32_bf16 v[10:13], v[240:243], v[216:219], v[10:13]
	v_mfma_f32_16x16x32_bf16 v[6:9], v[232:235], v[224:227], v[6:9]
	v_mfma_f32_16x16x32_bf16 v[2:5], v[240:243], v[224:227], v[2:5]
	s_setprio 0
	s_barrier
	ds_read_b128 v[180:183], v147
	ds_read_b128 v[184:187], v147 offset:1024
	ds_read_b128 v[188:191], v147 offset:2048
	ds_read_b128 v[192:195], v147 offset:3072
	v_lshl_add_u64 v[166:167], s[2:3], 0, v[246:247]
	s_add_i32 m0, s45, 0x4000
	ds_read_b128 v[196:199], v141 offset:32768
	ds_read_b128 v[200:203], v141 offset:33792
	ds_read_b128 v[204:207], v140 offset:32768
	ds_read_b128 v[208:211], v140 offset:33792
	ds_read_b128 v[212:215], v139 offset:32768
	ds_read_b128 v[216:219], v139 offset:33792
	ds_read_b128 v[220:223], v138 offset:32768
	ds_read_b128 v[224:227], v138 offset:33792
	global_load_lds_dwordx4 v[166:167], off
	s_add_i32 m0, s45, 0x6000
	v_lshl_add_u64 v[166:167], s[2:3], 0, v[248:249]
	global_load_lds_dwordx4 v[166:167], off
	s_waitcnt lgkmcnt(8)
	s_barrier
	s_waitcnt lgkmcnt(0)
	s_setprio 1
	v_mfma_f32_16x16x32_bf16 v[126:129], v[180:183], v[196:199], v[126:129]
	v_mfma_f32_16x16x32_bf16 v[122:125], v[188:191], v[196:199], v[122:125]
	v_mfma_f32_16x16x32_bf16 v[118:121], v[180:183], v[204:207], v[118:121]
	v_mfma_f32_16x16x32_bf16 v[114:117], v[188:191], v[204:207], v[114:117]
	v_mfma_f32_16x16x32_bf16 v[110:113], v[180:183], v[212:215], v[110:113]
	v_mfma_f32_16x16x32_bf16 v[106:109], v[188:191], v[212:215], v[106:109]
	v_mfma_f32_16x16x32_bf16 v[102:105], v[180:183], v[220:223], v[102:105]
	v_mfma_f32_16x16x32_bf16 v[98:101], v[188:191], v[220:223], v[98:101]
	v_mfma_f32_16x16x32_bf16 v[126:129], v[184:187], v[200:203], v[126:129]
	v_mfma_f32_16x16x32_bf16 v[122:125], v[192:195], v[200:203], v[122:125]
	v_mfma_f32_16x16x32_bf16 v[118:121], v[184:187], v[208:211], v[118:121]
	v_mfma_f32_16x16x32_bf16 v[114:117], v[192:195], v[208:211], v[114:117]
	v_mfma_f32_16x16x32_bf16 v[110:113], v[184:187], v[216:219], v[110:113]
	v_mfma_f32_16x16x32_bf16 v[106:109], v[192:195], v[216:219], v[106:109]
	v_mfma_f32_16x16x32_bf16 v[102:105], v[184:187], v[224:227], v[102:105]
	v_mfma_f32_16x16x32_bf16 v[98:101], v[192:195], v[224:227], v[98:101]
	s_setprio 0
	s_barrier
	v_add_u32_e32 v0, 0xc0, v252
	v_lshlrev_b64 v[166:167], 1, v[0:1]
	v_lshl_add_u64 v[244:245], s[6:7], 0, v[166:167]
	s_add_i32 m0, s45, 0x18000
	v_add_u32_e32 v0, 0xc0, v169
	ds_read_b128 v[228:231], v142
	ds_read_b128 v[232:235], v142 offset:1024
	ds_read_b128 v[236:239], v142 offset:2048
	ds_read_b128 v[240:243], v142 offset:3072
	global_load_lds_dwordx4 v[244:245], off
	v_lshlrev_b64 v[244:245], 1, v[0:1]
	s_add_i32 m0, s45, 0x1a000
	v_lshl_add_u64 v[246:247], s[6:7], 0, v[244:245]
	global_load_lds_dwordx4 v[246:247], off
	s_barrier
	s_waitcnt lgkmcnt(0)
	s_setprio 1
	v_mfma_f32_16x16x32_bf16 v[94:97], v[228:231], v[196:199], v[94:97]
	v_mfma_f32_16x16x32_bf16 v[90:93], v[236:239], v[196:199], v[90:93]
	v_mfma_f32_16x16x32_bf16 v[86:89], v[228:231], v[204:207], v[86:89]
	v_mfma_f32_16x16x32_bf16 v[82:85], v[236:239], v[204:207], v[82:85]
	v_mfma_f32_16x16x32_bf16 v[78:81], v[228:231], v[212:215], v[78:81]
	v_mfma_f32_16x16x32_bf16 v[74:77], v[236:239], v[212:215], v[74:77]
	v_mfma_f32_16x16x32_bf16 v[70:73], v[228:231], v[220:223], v[70:73]
	v_mfma_f32_16x16x32_bf16 v[66:69], v[236:239], v[220:223], v[66:69]
	v_mfma_f32_16x16x32_bf16 v[94:97], v[232:235], v[200:203], v[94:97]
	v_mfma_f32_16x16x32_bf16 v[90:93], v[240:243], v[200:203], v[90:93]
	v_mfma_f32_16x16x32_bf16 v[86:89], v[232:235], v[208:211], v[86:89]
	v_mfma_f32_16x16x32_bf16 v[82:85], v[240:243], v[208:211], v[82:85]
	v_mfma_f32_16x16x32_bf16 v[78:81], v[232:235], v[216:219], v[78:81]
	v_mfma_f32_16x16x32_bf16 v[74:77], v[240:243], v[216:219], v[74:77]
	v_mfma_f32_16x16x32_bf16 v[70:73], v[232:235], v[224:227], v[70:73]
	v_mfma_f32_16x16x32_bf16 v[66:69], v[240:243], v[224:227], v[66:69]
	s_setprio 0
	v_add_u32_e32 v0, 0xc0, v168
	v_lshl_add_u64 v[246:247], v[0:1], 1, s[4:5]
	s_add_i32 m0, s45, 0x8000
	v_add_u32_e32 v0, 0xc0, v179
	s_barrier
	ds_read_b128 v[196:199], v141 offset:49152
	ds_read_b128 v[200:203], v141 offset:50176
	ds_read_b128 v[204:207], v140 offset:49152
	ds_read_b128 v[208:211], v140 offset:50176
	ds_read_b128 v[212:215], v139 offset:49152
	ds_read_b128 v[216:219], v139 offset:50176
	ds_read_b128 v[220:223], v138 offset:49152
	ds_read_b128 v[224:227], v138 offset:50176
	global_load_lds_dwordx4 v[246:247], off
	s_add_i32 m0, s45, 0xa000
	v_lshl_add_u64 v[246:247], v[0:1], 1, s[4:5]
	global_load_lds_dwordx4 v[246:247], off
	s_barrier
; #define WAIT_V(n) asm volatile("s_waitcnt vmcnt(%0)" ::"n"(n) : "memory")
; #define WAIT_L(n) asm volatile("s_waitcnt lgkmcnt(%0)" ::"n"(n) : "memory")
; #define STAGE(P, BASE, OFF, kt) do { \
;     __builtin_amdgcn_global_load_lds((const unsigned*)((BASE) + (OFF[0] + (unsigned)(kt) * BK)), (unsigned*)((char*)(P) + wid * 1024), 16, 0, 0); \
;     __builtin_amdgcn_global_load_lds((const unsigned*)((BASE) + (OFF[1] + (unsigned)(kt) * BK)), (unsigned*)((char*)(P) + wid * 1024 + 8192), 16, 0, 0); } while (0)
; #define LDA(dst, b, h) for (int m = 0; m < 4; ++m) for (int k = 0; k < 2; ++k) \
;     dst[m][k] = *reinterpret_cast<const bf16x8*>((char*)SA(b, h) + lds_byte(wr * 64 + m * 16 + fr, k * 32 + fq * 8))
; #define LDB(dst, b, h) for (int n = 0; n < 2; ++n) for (int k = 0; k < 2; ++k) \
;     dst[n][k] = *reinterpret_cast<const bf16x8*>((char*)SB(b, h) + lds_byte(wc * 32 + n * 16 + fr, k * 32 + fq * 8))
; #define MMA(ai, bj, At_, Bt_) do { __builtin_amdgcn_s_setprio(1); \
;     for (int m = 0; m < 4; ++m) for (int n = 0; n < 2; ++n) for (int k = 0; k < 2; ++k) \
;       acc[ai][bj][m][n] = __builtin_amdgcn_mfma_f32_16x16x32_bf16(Bt_[n][k], At_[m][k], acc[ai][bj][m][n], 0, 0, 0); \
;     __builtin_amdgcn_s_setprio(0); } while (0)
; #define BAR __builtin_amdgcn_s_barrier()
; #define SCHED __builtin_amdgcn_sched_barrier(0)
; DEVI void gemm_tile(const Params& p, int layer, const u16* __restrict__ A, unsigned lda, const u16* __restrict__ Bt, unsigned ldb, int K,
;                     int brow, int bcol, int ekind, const int tid_) {
;     ...
;     BAR; WAIT_L(0); MMA(1, 0, At, B0); BAR; SCHED;
;     STAGE(SB(1, 1), B1p, offB, t + 3);
;     WAIT_V(6); BAR; MMA(1, 1, At, B1); BAR;
;   }
;   { LDB(B0, 0, 0); LDA(At, 0, 0); STAGE(SA(1, 1), A1, offA, nt - 1);
;     BAR; WAIT_L(0); MMA(0, 0, At, B0); BAR;
;     LDB(B1, 0, 1); BAR; WAIT_L(0); MMA(0, 1, At, B1); BAR;
	s_waitcnt lgkmcnt(0)
	s_setprio 1
	v_mfma_f32_16x16x32_bf16 v[62:65], v[180:183], v[196:199], v[62:65]
	v_mfma_f32_16x16x32_bf16 v[58:61], v[188:191], v[196:199], v[58:61]
	v_mfma_f32_16x16x32_bf16 v[54:57], v[180:183], v[204:207], v[54:57]
	v_mfma_f32_16x16x32_bf16 v[50:53], v[188:191], v[204:207], v[50:53]
	v_mfma_f32_16x16x32_bf16 v[46:49], v[180:183], v[212:215], v[46:49]
	v_mfma_f32_16x16x32_bf16 v[42:45], v[188:191], v[212:215], v[42:45]
	v_mfma_f32_16x16x32_bf16 v[38:41], v[180:183], v[220:223], v[38:41]
	v_mfma_f32_16x16x32_bf16 v[34:37], v[188:191], v[220:223], v[34:37]
	v_mfma_f32_16x16x32_bf16 v[62:65], v[184:187], v[200:203], v[62:65]
	v_mfma_f32_16x16x32_bf16 v[58:61], v[192:195], v[200:203], v[58:61]
	v_mfma_f32_16x16x32_bf16 v[54:57], v[184:187], v[208:211], v[54:57]
	v_mfma_f32_16x16x32_bf16 v[50:53], v[192:195], v[208:211], v[50:53]
	v_mfma_f32_16x16x32_bf16 v[46:49], v[184:187], v[216:219], v[46:49]
	v_mfma_f32_16x16x32_bf16 v[42:45], v[192:195], v[216:219], v[42:45]
	v_mfma_f32_16x16x32_bf16 v[38:41], v[184:187], v[224:227], v[38:41]
	v_mfma_f32_16x16x32_bf16 v[34:37], v[192:195], v[224:227], v[34:37]
	s_setprio 0
	s_barrier
	v_lshl_add_u64 v[166:167], s[8:9], 0, v[166:167]
	s_add_i32 m0, s45, 0x1c000
	s_nop 0
	global_load_lds_dwordx4 v[166:167], off
	s_add_i32 m0, s45, 0x1e000
	v_lshl_add_u64 v[166:167], s[8:9], 0, v[244:245]
	global_load_lds_dwordx4 v[166:167], off
	s_waitcnt vmcnt(6)
	s_barrier
	s_setprio 1
	v_mfma_f32_16x16x32_bf16 v[30:33], v[228:231], v[196:199], v[30:33]
	v_mfma_f32_16x16x32_bf16 v[26:29], v[236:239], v[196:199], v[26:29]
	v_mfma_f32_16x16x32_bf16 v[22:25], v[228:231], v[204:207], v[22:25]
	v_mfma_f32_16x16x32_bf16 v[18:21], v[236:239], v[204:207], v[18:21]
	v_mfma_f32_16x16x32_bf16 v[14:17], v[228:231], v[212:215], v[14:17]
	v_mfma_f32_16x16x32_bf16 v[10:13], v[236:239], v[212:215], v[10:13]
	v_mfma_f32_16x16x32_bf16 v[6:9], v[228:231], v[220:223], v[6:9]
	v_mfma_f32_16x16x32_bf16 v[2:5], v[236:239], v[220:223], v[2:5]
	v_mfma_f32_16x16x32_bf16 v[30:33], v[232:235], v[200:203], v[30:33]
	v_mfma_f32_16x16x32_bf16 v[26:29], v[240:243], v[200:203], v[26:29]
	v_mfma_f32_16x16x32_bf16 v[22:25], v[232:235], v[208:211], v[22:25]
	v_mfma_f32_16x16x32_bf16 v[18:21], v[240:243], v[208:211], v[18:21]
	v_mfma_f32_16x16x32_bf16 v[14:17], v[232:235], v[216:219], v[14:17]
	v_mfma_f32_16x16x32_bf16 v[10:13], v[240:243], v[216:219], v[10:13]
	v_mfma_f32_16x16x32_bf16 v[6:9], v[232:235], v[224:227], v[6:9]
	v_mfma_f32_16x16x32_bf16 v[2:5], v[240:243], v[224:227], v[2:5]
	s_setprio 0
	s_addk_i32 s11, 0x80
	s_cmp_lt_u32 s42, s10
	s_barrier
	s_cbranch_scc1 .LBB0_313
	s_sub_i32 s4, s66, 64
	v_add_u32_e32 v0, s4, v130
	v_readfirstlane_b32 s5, v164
	v_lshl_add_u64 v[144:145], v[0:1], 1, s[2:3]
	s_mov_b32 m0, s5
	v_add_u32_e32 v0, s4, v132
	ds_read_b128 v[148:151], v161
	ds_read_b128 v[152:155], v161 offset:1024
	ds_read_b128 v[180:183], v161 offset:2048
	ds_read_b128 v[158:161], v161 offset:3072
	ds_read_b128 v[184:187], v141
	ds_read_b128 v[188:191], v141 offset:1024
	ds_read_b128 v[192:195], v140
	ds_read_b128 v[196:199], v140 offset:1024
	ds_read_b128 v[200:203], v139
	ds_read_b128 v[204:207], v139 offset:1024
	ds_read_b128 v[208:211], v138
	ds_read_b128 v[212:215], v138 offset:1024
	global_load_lds_dwordx4 v[144:145], off
	v_lshl_add_u64 v[144:145], v[0:1], 1, s[2:3]
	v_readfirstlane_b32 s2, v165
	s_mov_b32 m0, s2
	s_nop 0
	global_load_lds_dwordx4 v[144:145], off
	s_barrier
	s_waitcnt lgkmcnt(0)
	s_setprio 1
	v_mfma_f32_16x16x32_bf16 v[126:129], v[148:151], v[184:187], v[126:129]
	v_mfma_f32_16x16x32_bf16 v[122:125], v[180:183], v[184:187], v[122:125]
	v_mfma_f32_16x16x32_bf16 v[118:121], v[148:151], v[192:195], v[118:121]
	v_mfma_f32_16x16x32_bf16 v[114:117], v[180:183], v[192:195], v[114:117]
	v_mfma_f32_16x16x32_bf16 v[102:105], v[148:151], v[208:211], v[102:105]
	v_mfma_f32_16x16x32_bf16 v[98:101], v[180:183], v[208:211], v[98:101]
	v_mfma_f32_16x16x32_bf16 v[126:129], v[152:155], v[188:191], v[126:129]
	v_mfma_f32_16x16x32_bf16 v[122:125], v[158:161], v[188:191], v[122:125]
	v_mfma_f32_16x16x32_bf16 v[118:121], v[152:155], v[196:199], v[118:121]
	v_mfma_f32_16x16x32_bf16 v[114:117], v[158:161], v[196:199], v[114:117]
	v_mfma_f32_16x16x32_bf16 v[110:113], v[148:151], v[200:203], v[110:113]
	v_mfma_f32_16x16x32_bf16 v[106:109], v[180:183], v[200:203], v[106:109]
	v_mfma_f32_16x16x32_bf16 v[102:105], v[152:155], v[212:215], v[102:105]
	v_mfma_f32_16x16x32_bf16 v[98:101], v[158:161], v[212:215], v[98:101]
	v_mfma_f32_16x16x32_bf16 v[162:165], v[152:155], v[204:207], v[110:113]
	v_mfma_f32_16x16x32_bf16 v[216:219], v[158:161], v[204:207], v[106:109]
	s_setprio 0
	s_barrier
	s_nop 1
	ds_read_b128 v[106:109], v156
	ds_read_b128 v[110:113], v156 offset:1024
	ds_read_b128 v[220:223], v156 offset:2048
	ds_read_b128 v[224:227], v156 offset:3072
	s_barrier
	s_waitcnt lgkmcnt(0)
	s_setprio 1
	v_mfma_f32_16x16x32_bf16 v[86:89], v[106:109], v[192:195], v[86:89]
	v_mfma_f32_16x16x32_bf16 v[82:85], v[220:223], v[192:195], v[82:85]
	v_mfma_f32_16x16x32_bf16 v[70:73], v[106:109], v[208:211], v[70:73]
	v_mfma_f32_16x16x32_bf16 v[66:69], v[220:223], v[208:211], v[66:69]
	v_mfma_f32_16x16x32_bf16 v[94:97], v[106:109], v[184:187], v[94:97]
	v_mfma_f32_16x16x32_bf16 v[90:93], v[220:223], v[184:187], v[90:93]
	v_mfma_f32_16x16x32_bf16 v[86:89], v[110:113], v[196:199], v[86:89]
	v_mfma_f32_16x16x32_bf16 v[82:85], v[224:227], v[196:199], v[82:85]
	v_mfma_f32_16x16x32_bf16 v[78:81], v[106:109], v[200:203], v[78:81]
	v_mfma_f32_16x16x32_bf16 v[74:77], v[220:223], v[200:203], v[74:77]
	v_mfma_f32_16x16x32_bf16 v[70:73], v[110:113], v[212:215], v[70:73]
	v_mfma_f32_16x16x32_bf16 v[66:69], v[224:227], v[212:215], v[66:69]
	v_mfma_f32_16x16x32_bf16 v[228:231], v[110:113], v[188:191], v[94:97]
	v_mfma_f32_16x16x32_bf16 v[184:187], v[224:227], v[188:191], v[90:93]
	v_mfma_f32_16x16x32_bf16 v[188:191], v[110:113], v[204:207], v[78:81]
	v_mfma_f32_16x16x32_bf16 v[192:195], v[224:227], v[204:207], v[74:77]
	s_setprio 0
	s_barrier
; #define WAIT_V(n) asm volatile("s_waitcnt vmcnt(%0)" ::"n"(n) : "memory")
; #define WAIT_L(n) asm volatile("s_waitcnt lgkmcnt(%0)" ::"n"(n) : "memory")
; #define LDA(dst, b, h) for (int m = 0; m < 4; ++m) for (int k = 0; k < 2; ++k) \
;     dst[m][k] = *reinterpret_cast<const bf16x8*>((char*)SA(b, h) + lds_byte(wr * 64 + m * 16 + fr, k * 32 + fq * 8))
; #define LDB(dst, b, h) for (int n = 0; n < 2; ++n) for (int k = 0; k < 2; ++k) \
;     dst[n][k] = *reinterpret_cast<const bf16x8*>((char*)SB(b, h) + lds_byte(wc * 32 + n * 16 + fr, k * 32 + fq * 8))
; #define MMA(ai, bj, At_, Bt_) do { __builtin_amdgcn_s_setprio(1); \
;     for (int m = 0; m < 4; ++m) for (int n = 0; n < 2; ++n) for (int k = 0; k < 2; ++k) \
;       acc[ai][bj][m][n] = __builtin_amdgcn_mfma_f32_16x16x32_bf16(Bt_[n][k], At_[m][k], acc[ai][bj][m][n], 0, 0, 0); \
;     __builtin_amdgcn_s_setprio(0); } while (0)
; #define BAR __builtin_amdgcn_s_barrier()
; DEVI void gemm_tile(const Params& p, int layer, const u16* __restrict__ A, unsigned lda, const u16* __restrict__ Bt, unsigned ldb, int K,
;                     int brow, int bcol, int ekind, const int tid_) {
;     ...
;     LDA(At, 0, 1); WAIT_V(4); BAR; WAIT_L(0); MMA(1, 0, At, B0); MMA(1, 1, At, B1); BAR; }
;   { LDB(B0, 1, 0); LDA(At, 1, 0); WAIT_V(2); BAR; WAIT_L(0); MMA(0, 0, At, B0); BAR;
	s_nop 0
	ds_read_b128 v[74:77], v141 offset:16384
	ds_read_b128 v[78:81], v141 offset:17408
	ds_read_b128 v[90:93], v140 offset:16384
	ds_read_b128 v[94:97], v140 offset:17408
	ds_read_b128 v[196:199], v139 offset:16384
	ds_read_b128 v[200:203], v139 offset:17408
	ds_read_b128 v[204:207], v138 offset:16384
	ds_read_b128 v[208:211], v138 offset:17408
	s_waitcnt vmcnt(4)
	s_barrier
	s_waitcnt lgkmcnt(0)
	s_setprio 1
	v_mfma_f32_16x16x32_bf16 v[62:65], v[148:151], v[74:77], v[62:65]
	v_mfma_f32_16x16x32_bf16 v[58:61], v[180:183], v[74:77], v[58:61]
	v_mfma_f32_16x16x32_bf16 v[54:57], v[148:151], v[90:93], v[54:57]
	v_mfma_f32_16x16x32_bf16 v[50:53], v[180:183], v[90:93], v[50:53]
	v_mfma_f32_16x16x32_bf16 v[38:41], v[148:151], v[204:207], v[38:41]
	v_mfma_f32_16x16x32_bf16 v[34:37], v[180:183], v[204:207], v[34:37]
	v_mfma_f32_16x16x32_bf16 v[62:65], v[152:155], v[78:81], v[62:65]
	v_mfma_f32_16x16x32_bf16 v[58:61], v[158:161], v[78:81], v[58:61]
	v_mfma_f32_16x16x32_bf16 v[54:57], v[152:155], v[94:97], v[54:57]
	v_mfma_f32_16x16x32_bf16 v[50:53], v[158:161], v[94:97], v[50:53]
	v_mfma_f32_16x16x32_bf16 v[46:49], v[148:151], v[196:199], v[46:49]
	v_mfma_f32_16x16x32_bf16 v[42:45], v[180:183], v[196:199], v[42:45]
	v_mfma_f32_16x16x32_bf16 v[38:41], v[152:155], v[208:211], v[38:41]
	v_mfma_f32_16x16x32_bf16 v[34:37], v[158:161], v[208:211], v[34:37]
	v_mfma_f32_16x16x32_bf16 v[212:215], v[152:155], v[200:203], v[46:49]
	v_mfma_f32_16x16x32_bf16 v[232:235], v[158:161], v[200:203], v[42:45]
	s_setprio 0
	s_setprio 1
	v_mfma_f32_16x16x32_bf16 v[22:25], v[106:109], v[90:93], v[22:25]
	v_mfma_f32_16x16x32_bf16 v[18:21], v[220:223], v[90:93], v[18:21]
	v_mfma_f32_16x16x32_bf16 v[6:9], v[106:109], v[204:207], v[6:9]
	v_mfma_f32_16x16x32_bf16 v[2:5], v[220:223], v[204:207], v[2:5]
	v_mfma_f32_16x16x32_bf16 v[30:33], v[106:109], v[74:77], v[30:33]
	v_mfma_f32_16x16x32_bf16 v[26:29], v[220:223], v[74:77], v[26:29]
	v_mfma_f32_16x16x32_bf16 v[22:25], v[110:113], v[94:97], v[22:25]
	v_mfma_f32_16x16x32_bf16 v[18:21], v[224:227], v[94:97], v[18:21]
	v_mfma_f32_16x16x32_bf16 v[14:17], v[106:109], v[196:199], v[14:17]
	v_mfma_f32_16x16x32_bf16 v[10:13], v[220:223], v[196:199], v[10:13]
	v_mfma_f32_16x16x32_bf16 v[6:9], v[110:113], v[208:211], v[6:9]
	v_mfma_f32_16x16x32_bf16 v[2:5], v[224:227], v[208:211], v[2:5]
	v_mfma_f32_16x16x32_bf16 v[148:151], v[110:113], v[78:81], v[30:33]
	v_mfma_f32_16x16x32_bf16 v[152:155], v[224:227], v[78:81], v[26:29]
	v_mfma_f32_16x16x32_bf16 v[156:159], v[110:113], v[200:203], v[14:17]
	v_mfma_f32_16x16x32_bf16 v[180:183], v[224:227], v[200:203], v[10:13]
	s_setprio 0
	s_barrier
	s_nop 0
	ds_read_b128 v[10:13], v147
	ds_read_b128 v[14:17], v147 offset:1024
	ds_read_b128 v[196:199], v147 offset:2048
	ds_read_b128 v[200:203], v147 offset:3072
	ds_read_b128 v[26:29], v141 offset:32768
	ds_read_b128 v[30:33], v141 offset:33792
	ds_read_b128 v[42:45], v140 offset:32768
	ds_read_b128 v[46:49], v140 offset:33792
	ds_read_b128 v[204:207], v139 offset:32768
	ds_read_b128 v[208:211], v139 offset:33792
	ds_read_b128 v[220:223], v138 offset:32768
	ds_read_b128 v[224:227], v138 offset:33792
	s_waitcnt vmcnt(2)
	s_barrier
	s_waitcnt lgkmcnt(0)
	s_setprio 1
	v_mfma_f32_16x16x32_bf16 v[74:77], v[10:13], v[26:29], v[126:129]
	v_mfma_f32_16x16x32_bf16 v[126:129], v[14:17], v[30:33], v[74:77]
	v_mfma_f32_16x16x32_bf16 v[74:77], v[196:199], v[26:29], v[122:125]
	v_mfma_f32_16x16x32_bf16 v[122:125], v[200:203], v[30:33], v[74:77]
	v_mfma_f32_16x16x32_bf16 v[74:77], v[10:13], v[42:45], v[118:121]
	v_mfma_f32_16x16x32_bf16 v[110:113], v[14:17], v[46:49], v[74:77]
	v_mfma_f32_16x16x32_bf16 v[74:77], v[196:199], v[42:45], v[114:117]
	v_mfma_f32_16x16x32_bf16 v[106:109], v[200:203], v[46:49], v[74:77]
	v_mfma_f32_16x16x32_bf16 v[74:77], v[10:13], v[204:207], v[162:165]
	v_mfma_f32_16x16x32_bf16 v[94:97], v[14:17], v[208:211], v[74:77]
	v_mfma_f32_16x16x32_bf16 v[74:77], v[196:199], v[204:207], v[216:219]
	v_mfma_f32_16x16x32_bf16 v[90:93], v[200:203], v[208:211], v[74:77]
	v_mfma_f32_16x16x32_bf16 v[74:77], v[10:13], v[220:223], v[102:105]
	v_mfma_f32_16x16x32_bf16 v[78:81], v[14:17], v[224:227], v[74:77]
	v_mfma_f32_16x16x32_bf16 v[74:77], v[196:199], v[220:223], v[98:101]
	v_mfma_f32_16x16x32_bf16 v[74:77], v[200:203], v[224:227], v[74:77]
	s_setprio 0
	s_barrier
; #define WAIT_V(n) asm volatile("s_waitcnt vmcnt(%0)" ::"n"(n) : "memory")
; #define WAIT_L(n) asm volatile("s_waitcnt lgkmcnt(%0)" ::"n"(n) : "memory")
; #define LDA(dst, b, h) for (int m = 0; m < 4; ++m) for (int k = 0; k < 2; ++k) \
;     dst[m][k] = *reinterpret_cast<const bf16x8*>((char*)SA(b, h) + lds_byte(wr * 64 + m * 16 + fr, k * 32 + fq * 8))
; #define LDB(dst, b, h) for (int n = 0; n < 2; ++n) for (int k = 0; k < 2; ++k) \
;     dst[n][k] = *reinterpret_cast<const bf16x8*>((char*)SB(b, h) + lds_byte(wc * 32 + n * 16 + fr, k * 32 + fq * 8))
; #define MMA(ai, bj, At_, Bt_) do { __builtin_amdgcn_s_setprio(1); \
;     for (int m = 0; m < 4; ++m) for (int n = 0; n < 2; ++n) for (int k = 0; k < 2; ++k) \
;       acc[ai][bj][m][n] = __builtin_amdgcn_mfma_f32_16x16x32_bf16(Bt_[n][k], At_[m][k], acc[ai][bj][m][n], 0, 0, 0); \
;     __builtin_amdgcn_s_setprio(0); } while (0)
; #define BAR __builtin_amdgcn_s_barrier()
; DEVI void gemm_tile(const Params& p, int layer, const u16* __restrict__ A, unsigned lda, const u16* __restrict__ Bt, unsigned ldb, int K,
;                     int brow, int bcol, int ekind, const int tid_) {
;     ...
;   { LDB(B0, 1, 0); LDA(At, 1, 0); WAIT_V(2); BAR; WAIT_L(0); MMA(0, 0, At, B0); BAR;
;     LDB(B1, 1, 1); WAIT_V(0); BAR; WAIT_L(0); MMA(0, 1, At, B1); BAR;
;     LDA(At, 1, 1); BAR; WAIT_L(0); MMA(1, 0, At, B0); MMA(1, 1, At, B1); BAR; }
;   if (wr == 0) BAR;
	ds_read_b128 v[160:163], v142
	ds_read_b128 v[164:167], v142 offset:1024
	ds_read_b128 v[216:219], v142 offset:2048
	ds_read_b128 v[142:145], v142 offset:3072
	s_waitcnt vmcnt(0)
	s_barrier
	s_waitcnt lgkmcnt(0)
	s_setprio 1
	v_mfma_f32_16x16x32_bf16 v[98:101], v[160:163], v[26:29], v[228:231]
	v_mfma_f32_16x16x32_bf16 v[26:29], v[216:219], v[26:29], v[184:187]
	v_mfma_f32_16x16x32_bf16 v[114:117], v[142:145], v[30:33], v[26:29]
	v_mfma_f32_16x16x32_bf16 v[26:29], v[160:163], v[42:45], v[86:89]
	v_mfma_f32_16x16x32_bf16 v[102:105], v[164:167], v[46:49], v[26:29]
	v_mfma_f32_16x16x32_bf16 v[26:29], v[216:219], v[42:45], v[82:85]
	v_mfma_f32_16x16x32_bf16 v[118:121], v[164:167], v[30:33], v[98:101]
	v_mfma_f32_16x16x32_bf16 v[98:101], v[142:145], v[46:49], v[26:29]
	v_mfma_f32_16x16x32_bf16 v[26:29], v[160:163], v[204:207], v[188:191]
	v_mfma_f32_16x16x32_bf16 v[86:89], v[164:167], v[208:211], v[26:29]
	v_mfma_f32_16x16x32_bf16 v[26:29], v[216:219], v[204:207], v[192:195]
	v_mfma_f32_16x16x32_bf16 v[82:85], v[142:145], v[208:211], v[26:29]
	v_mfma_f32_16x16x32_bf16 v[26:29], v[160:163], v[220:223], v[70:73]
	v_mfma_f32_16x16x32_bf16 v[70:73], v[164:167], v[224:227], v[26:29]
	v_mfma_f32_16x16x32_bf16 v[26:29], v[216:219], v[220:223], v[66:69]
	v_mfma_f32_16x16x32_bf16 v[66:69], v[142:145], v[224:227], v[26:29]
	s_setprio 0
	s_barrier
	ds_read_b128 v[184:187], v141 offset:49152
	ds_read_b128 v[188:191], v141 offset:50176
	ds_read_b128 v[192:195], v140 offset:49152
	ds_read_b128 v[204:207], v140 offset:50176
	ds_read_b128 v[208:211], v139 offset:49152
	ds_read_b128 v[220:223], v139 offset:50176
	ds_read_b128 v[224:227], v138 offset:49152
	ds_read_b128 v[138:141], v138 offset:50176
	s_barrier
	s_waitcnt lgkmcnt(0)
	s_setprio 1
	v_mfma_f32_16x16x32_bf16 v[26:29], v[10:13], v[184:187], v[62:65]
	v_mfma_f32_16x16x32_bf16 v[62:65], v[14:17], v[188:191], v[26:29]
	v_mfma_f32_16x16x32_bf16 v[26:29], v[196:199], v[184:187], v[58:61]
	v_mfma_f32_16x16x32_bf16 v[58:61], v[200:203], v[188:191], v[26:29]
	v_mfma_f32_16x16x32_bf16 v[26:29], v[10:13], v[192:195], v[54:57]
	v_mfma_f32_16x16x32_bf16 v[46:49], v[14:17], v[204:207], v[26:29]
	v_mfma_f32_16x16x32_bf16 v[26:29], v[196:199], v[192:195], v[50:53]
	v_mfma_f32_16x16x32_bf16 v[42:45], v[200:203], v[204:207], v[26:29]
	v_mfma_f32_16x16x32_bf16 v[26:29], v[10:13], v[208:211], v[212:215]
	v_mfma_f32_16x16x32_bf16 v[10:13], v[10:13], v[224:227], v[38:41]
	v_mfma_f32_16x16x32_bf16 v[30:33], v[14:17], v[220:223], v[26:29]
	v_mfma_f32_16x16x32_bf16 v[26:29], v[196:199], v[208:211], v[232:235]
	v_mfma_f32_16x16x32_bf16 v[14:17], v[14:17], v[138:141], v[10:13]
	v_mfma_f32_16x16x32_bf16 v[10:13], v[196:199], v[224:227], v[34:37]
	v_mfma_f32_16x16x32_bf16 v[26:29], v[200:203], v[220:223], v[26:29]
	v_mfma_f32_16x16x32_bf16 v[10:13], v[200:203], v[138:141], v[10:13]
	s_setprio 0
	s_setprio 1
	v_mfma_f32_16x16x32_bf16 v[34:37], v[160:163], v[184:187], v[148:151]
	v_mfma_f32_16x16x32_bf16 v[54:57], v[164:167], v[188:191], v[34:37]
	v_mfma_f32_16x16x32_bf16 v[34:37], v[216:219], v[184:187], v[152:155]
	v_mfma_f32_16x16x32_bf16 v[18:21], v[216:219], v[192:195], v[18:21]
	v_mfma_f32_16x16x32_bf16 v[50:53], v[142:145], v[188:191], v[34:37]
	v_mfma_f32_16x16x32_bf16 v[22:25], v[160:163], v[192:195], v[22:25]
	v_mfma_f32_16x16x32_bf16 v[34:37], v[142:145], v[204:207], v[18:21]
	v_mfma_f32_16x16x32_bf16 v[18:21], v[160:163], v[208:211], v[156:159]
	v_mfma_f32_16x16x32_bf16 v[38:41], v[164:167], v[204:207], v[22:25]
	v_mfma_f32_16x16x32_bf16 v[22:25], v[164:167], v[220:223], v[18:21]
	v_mfma_f32_16x16x32_bf16 v[18:21], v[216:219], v[208:211], v[180:183]
	v_mfma_f32_16x16x32_bf16 v[6:9], v[160:163], v[224:227], v[6:9]
	v_mfma_f32_16x16x32_bf16 v[2:5], v[216:219], v[224:227], v[2:5]
	v_mfma_f32_16x16x32_bf16 v[18:21], v[142:145], v[220:223], v[18:21]
	v_mfma_f32_16x16x32_bf16 v[6:9], v[164:167], v[138:141], v[6:9]
	v_mfma_f32_16x16x32_bf16 v[2:5], v[142:145], v[138:141], v[2:5]
	s_setprio 0
	s_movk_i32 s2, 0x100
	v_cmp_gt_u32_e32 vcc, s2, v136
	s_barrier
	s_and_saveexec_b64 s[2:3], vcc
	s_cbranch_execz .LBB0_316
	s_barrier
